# c47 + phase-0 softmax-bound item: the 384-entry rel_bias max is read with 96 pipelined dwordx4 loads (16 in flight) instead of 192 load-wait-max iterations
# baseline (speedup 1.0000x reference)
; __device__ void phase0(const Params& p, unsigned char* smem) {
;     ...
;             if (tid < 2) {
;                 const int l = tid; float mqa = 0.f, mka = 0.f, mqb = 0.f, mkb = 0.f, mb = 0.f;
;                 for (int i = 0; i < 64; ++i) { mqa = fmaxf(mqa, fabsf(p.q_norm_a[l * 64 + i])); mka = fmaxf(mka, fabsf(p.k_norm_a[l * 64 + i]));
;                     mqb = fmaxf(mqb, fabsf(p.q_norm_b[l * 64 + i])); mkb = fmaxf(mkb, fabsf(p.k_norm_b[l * 64 + i])); }
;                 for (int i = 0; i < 32 * 12; ++i) mb = fmaxf(mb, p.rel_bias[i]);
;                 float* bd = (float*)(p.ws + WS_BND);
;                 bd[l] = 8.f * mqa * mka * LOG2E; bd[2 + l] = (8.f * mqb * mkb + mb) * LOG2E;
;             }
.LBB0_166:
	v_mov_b32_e32 v6, 0
	v_mov_b32_e32 v7, 0
	global_load_dwordx4 v[112:115], v21, s[38:39] offset:0
	global_load_dwordx4 v[116:119], v21, s[38:39] offset:16
	global_load_dwordx4 v[120:123], v21, s[38:39] offset:32
	global_load_dwordx4 v[124:127], v21, s[38:39] offset:48
	global_load_dwordx4 v[128:131], v21, s[38:39] offset:64
	global_load_dwordx4 v[132:135], v21, s[38:39] offset:80
	global_load_dwordx4 v[136:139], v21, s[38:39] offset:96
	global_load_dwordx4 v[140:143], v21, s[38:39] offset:112
	global_load_dwordx4 v[144:147], v21, s[38:39] offset:128
	global_load_dwordx4 v[148:151], v21, s[38:39] offset:144
	global_load_dwordx4 v[152:155], v21, s[38:39] offset:160
	global_load_dwordx4 v[156:159], v21, s[38:39] offset:176
	global_load_dwordx4 v[160:163], v21, s[38:39] offset:192
	global_load_dwordx4 v[164:167], v21, s[38:39] offset:208
	global_load_dwordx4 v[168:171], v21, s[38:39] offset:224
	global_load_dwordx4 v[172:175], v21, s[38:39] offset:240
	s_waitcnt vmcnt(15)
	v_max_f32_e32 v112, v112, v112
	v_max_f32_e32 v113, v113, v113
	v_max_f32_e32 v114, v114, v114
	v_max_f32_e32 v115, v115, v115
	v_max_f32_e32 v6, v6, v112
	v_max_f32_e32 v7, v7, v113
	v_max_f32_e32 v6, v6, v114
	v_max_f32_e32 v7, v7, v115
	global_load_dwordx4 v[112:115], v21, s[38:39] offset:256
	s_waitcnt vmcnt(15)
	v_max_f32_e32 v116, v116, v116
	v_max_f32_e32 v117, v117, v117
	v_max_f32_e32 v118, v118, v118
	v_max_f32_e32 v119, v119, v119
	v_max_f32_e32 v6, v6, v116
	v_max_f32_e32 v7, v7, v117
	v_max_f32_e32 v6, v6, v118
	v_max_f32_e32 v7, v7, v119
	global_load_dwordx4 v[116:119], v21, s[38:39] offset:272
	s_waitcnt vmcnt(15)
	v_max_f32_e32 v120, v120, v120
	v_max_f32_e32 v121, v121, v121
	v_max_f32_e32 v122, v122, v122
	v_max_f32_e32 v123, v123, v123
	v_max_f32_e32 v6, v6, v120
	v_max_f32_e32 v7, v7, v121
	v_max_f32_e32 v6, v6, v122
	v_max_f32_e32 v7, v7, v123
	global_load_dwordx4 v[120:123], v21, s[38:39] offset:288
	s_waitcnt vmcnt(15)
	v_max_f32_e32 v124, v124, v124
	v_max_f32_e32 v125, v125, v125
	v_max_f32_e32 v126, v126, v126
	v_max_f32_e32 v127, v127, v127
	v_max_f32_e32 v6, v6, v124
	v_max_f32_e32 v7, v7, v125
	v_max_f32_e32 v6, v6, v126
	v_max_f32_e32 v7, v7, v127
	global_load_dwordx4 v[124:127], v21, s[38:39] offset:304
	s_waitcnt vmcnt(15)
	v_max_f32_e32 v128, v128, v128
	v_max_f32_e32 v129, v129, v129
	v_max_f32_e32 v130, v130, v130
	v_max_f32_e32 v131, v131, v131
	v_max_f32_e32 v6, v6, v128
	v_max_f32_e32 v7, v7, v129
	v_max_f32_e32 v6, v6, v130
	v_max_f32_e32 v7, v7, v131
	global_load_dwordx4 v[128:131], v21, s[38:39] offset:320
	s_waitcnt vmcnt(15)
	v_max_f32_e32 v132, v132, v132
	v_max_f32_e32 v133, v133, v133
	v_max_f32_e32 v134, v134, v134
	v_max_f32_e32 v135, v135, v135
	v_max_f32_e32 v6, v6, v132
	v_max_f32_e32 v7, v7, v133
	v_max_f32_e32 v6, v6, v134
	v_max_f32_e32 v7, v7, v135
	global_load_dwordx4 v[132:135], v21, s[38:39] offset:336
	s_waitcnt vmcnt(15)
	v_max_f32_e32 v136, v136, v136
	v_max_f32_e32 v137, v137, v137
	v_max_f32_e32 v138, v138, v138
	v_max_f32_e32 v139, v139, v139
	v_max_f32_e32 v6, v6, v136
	v_max_f32_e32 v7, v7, v137
	v_max_f32_e32 v6, v6, v138
	v_max_f32_e32 v7, v7, v139
	global_load_dwordx4 v[136:139], v21, s[38:39] offset:352
	s_waitcnt vmcnt(15)
	v_max_f32_e32 v140, v140, v140
	v_max_f32_e32 v141, v141, v141
	v_max_f32_e32 v142, v142, v142
	v_max_f32_e32 v143, v143, v143
	v_max_f32_e32 v6, v6, v140
	v_max_f32_e32 v7, v7, v141
	v_max_f32_e32 v6, v6, v142
	v_max_f32_e32 v7, v7, v143
	global_load_dwordx4 v[140:143], v21, s[38:39] offset:368
	s_waitcnt vmcnt(15)
	v_max_f32_e32 v144, v144, v144
	v_max_f32_e32 v145, v145, v145
	v_max_f32_e32 v146, v146, v146
	v_max_f32_e32 v147, v147, v147
	v_max_f32_e32 v6, v6, v144
	v_max_f32_e32 v7, v7, v145
	v_max_f32_e32 v6, v6, v146
	v_max_f32_e32 v7, v7, v147
	global_load_dwordx4 v[144:147], v21, s[38:39] offset:384
	s_waitcnt vmcnt(15)
	v_max_f32_e32 v148, v148, v148
	v_max_f32_e32 v149, v149, v149
	v_max_f32_e32 v150, v150, v150
	v_max_f32_e32 v151, v151, v151
	v_max_f32_e32 v6, v6, v148
	v_max_f32_e32 v7, v7, v149
	v_max_f32_e32 v6, v6, v150
	v_max_f32_e32 v7, v7, v151
	global_load_dwordx4 v[148:151], v21, s[38:39] offset:400
	s_waitcnt vmcnt(15)
	v_max_f32_e32 v152, v152, v152
	v_max_f32_e32 v153, v153, v153
	v_max_f32_e32 v154, v154, v154
	v_max_f32_e32 v155, v155, v155
	v_max_f32_e32 v6, v6, v152
	v_max_f32_e32 v7, v7, v153
	v_max_f32_e32 v6, v6, v154
	v_max_f32_e32 v7, v7, v155
	global_load_dwordx4 v[152:155], v21, s[38:39] offset:416
	s_waitcnt vmcnt(15)
	v_max_f32_e32 v156, v156, v156
	v_max_f32_e32 v157, v157, v157
	v_max_f32_e32 v158, v158, v158
	v_max_f32_e32 v159, v159, v159
	v_max_f32_e32 v6, v6, v156
	v_max_f32_e32 v7, v7, v157
	v_max_f32_e32 v6, v6, v158
	v_max_f32_e32 v7, v7, v159
	global_load_dwordx4 v[156:159], v21, s[38:39] offset:432
	s_waitcnt vmcnt(15)
	v_max_f32_e32 v160, v160, v160
	v_max_f32_e32 v161, v161, v161
	v_max_f32_e32 v162, v162, v162
	v_max_f32_e32 v163, v163, v163
	v_max_f32_e32 v6, v6, v160
	v_max_f32_e32 v7, v7, v161
	v_max_f32_e32 v6, v6, v162
	v_max_f32_e32 v7, v7, v163
	global_load_dwordx4 v[160:163], v21, s[38:39] offset:448
	s_waitcnt vmcnt(15)
	v_max_f32_e32 v164, v164, v164
	v_max_f32_e32 v165, v165, v165
	v_max_f32_e32 v166, v166, v166
	v_max_f32_e32 v167, v167, v167
	v_max_f32_e32 v6, v6, v164
	v_max_f32_e32 v7, v7, v165
	v_max_f32_e32 v6, v6, v166
	v_max_f32_e32 v7, v7, v167
	global_load_dwordx4 v[164:167], v21, s[38:39] offset:464
	s_waitcnt vmcnt(15)
	v_max_f32_e32 v168, v168, v168
	v_max_f32_e32 v169, v169, v169
	v_max_f32_e32 v170, v170, v170
	v_max_f32_e32 v171, v171, v171
	v_max_f32_e32 v6, v6, v168
	v_max_f32_e32 v7, v7, v169
	v_max_f32_e32 v6, v6, v170
	v_max_f32_e32 v7, v7, v171
	global_load_dwordx4 v[168:171], v21, s[38:39] offset:480
	s_waitcnt vmcnt(15)
; __device__ void phase0(const Params& p, unsigned char* smem) {
;     ...
;             if (tid < 2) {
;                 const int l = tid; float mqa = 0.f, mka = 0.f, mqb = 0.f, mkb = 0.f, mb = 0.f;
;                 for (int i = 0; i < 64; ++i) { mqa = fmaxf(mqa, fabsf(p.q_norm_a[l * 64 + i])); mka = fmaxf(mka, fabsf(p.k_norm_a[l * 64 + i]));
;                     mqb = fmaxf(mqb, fabsf(p.q_norm_b[l * 64 + i])); mkb = fmaxf(mkb, fabsf(p.k_norm_b[l * 64 + i])); }
;                 for (int i = 0; i < 32 * 12; ++i) mb = fmaxf(mb, p.rel_bias[i]);
;                 float* bd = (float*)(p.ws + WS_BND);
;                 bd[l] = 8.f * mqa * mka * LOG2E; bd[2 + l] = (8.f * mqb * mkb + mb) * LOG2E;
;             }
	v_max_f32_e32 v172, v172, v172
	v_max_f32_e32 v173, v173, v173
	v_max_f32_e32 v174, v174, v174
	v_max_f32_e32 v175, v175, v175
	v_max_f32_e32 v6, v6, v172
	v_max_f32_e32 v7, v7, v173
	v_max_f32_e32 v6, v6, v174
	v_max_f32_e32 v7, v7, v175
	global_load_dwordx4 v[172:175], v21, s[38:39] offset:496
	s_waitcnt vmcnt(15)
	v_max_f32_e32 v112, v112, v112
	v_max_f32_e32 v113, v113, v113
	v_max_f32_e32 v114, v114, v114
	v_max_f32_e32 v115, v115, v115
	v_max_f32_e32 v6, v6, v112
	v_max_f32_e32 v7, v7, v113
	v_max_f32_e32 v6, v6, v114
	v_max_f32_e32 v7, v7, v115
	global_load_dwordx4 v[112:115], v21, s[38:39] offset:512
	s_waitcnt vmcnt(15)
	v_max_f32_e32 v116, v116, v116
	v_max_f32_e32 v117, v117, v117
	v_max_f32_e32 v118, v118, v118
	v_max_f32_e32 v119, v119, v119
	v_max_f32_e32 v6, v6, v116
	v_max_f32_e32 v7, v7, v117
	v_max_f32_e32 v6, v6, v118
	v_max_f32_e32 v7, v7, v119
	global_load_dwordx4 v[116:119], v21, s[38:39] offset:528
	s_waitcnt vmcnt(15)
	v_max_f32_e32 v120, v120, v120
	v_max_f32_e32 v121, v121, v121
	v_max_f32_e32 v122, v122, v122
	v_max_f32_e32 v123, v123, v123
	v_max_f32_e32 v6, v6, v120
	v_max_f32_e32 v7, v7, v121
	v_max_f32_e32 v6, v6, v122
	v_max_f32_e32 v7, v7, v123
	global_load_dwordx4 v[120:123], v21, s[38:39] offset:544
	s_waitcnt vmcnt(15)
	v_max_f32_e32 v124, v124, v124
	v_max_f32_e32 v125, v125, v125
	v_max_f32_e32 v126, v126, v126
	v_max_f32_e32 v127, v127, v127
	v_max_f32_e32 v6, v6, v124
	v_max_f32_e32 v7, v7, v125
	v_max_f32_e32 v6, v6, v126
	v_max_f32_e32 v7, v7, v127
	global_load_dwordx4 v[124:127], v21, s[38:39] offset:560
	s_waitcnt vmcnt(15)
	v_max_f32_e32 v128, v128, v128
	v_max_f32_e32 v129, v129, v129
	v_max_f32_e32 v130, v130, v130
	v_max_f32_e32 v131, v131, v131
	v_max_f32_e32 v6, v6, v128
	v_max_f32_e32 v7, v7, v129
	v_max_f32_e32 v6, v6, v130
	v_max_f32_e32 v7, v7, v131
	global_load_dwordx4 v[128:131], v21, s[38:39] offset:576
	s_waitcnt vmcnt(15)
	v_max_f32_e32 v132, v132, v132
	v_max_f32_e32 v133, v133, v133
	v_max_f32_e32 v134, v134, v134
	v_max_f32_e32 v135, v135, v135
	v_max_f32_e32 v6, v6, v132
	v_max_f32_e32 v7, v7, v133
	v_max_f32_e32 v6, v6, v134
	v_max_f32_e32 v7, v7, v135
	global_load_dwordx4 v[132:135], v21, s[38:39] offset:592
	s_waitcnt vmcnt(15)
	v_max_f32_e32 v136, v136, v136
	v_max_f32_e32 v137, v137, v137
	v_max_f32_e32 v138, v138, v138
	v_max_f32_e32 v139, v139, v139
	v_max_f32_e32 v6, v6, v136
	v_max_f32_e32 v7, v7, v137
	v_max_f32_e32 v6, v6, v138
	v_max_f32_e32 v7, v7, v139
	global_load_dwordx4 v[136:139], v21, s[38:39] offset:608
	s_waitcnt vmcnt(15)
	v_max_f32_e32 v140, v140, v140
	v_max_f32_e32 v141, v141, v141
	v_max_f32_e32 v142, v142, v142
	v_max_f32_e32 v143, v143, v143
	v_max_f32_e32 v6, v6, v140
	v_max_f32_e32 v7, v7, v141
	v_max_f32_e32 v6, v6, v142
	v_max_f32_e32 v7, v7, v143
	global_load_dwordx4 v[140:143], v21, s[38:39] offset:624
	s_waitcnt vmcnt(15)
	v_max_f32_e32 v144, v144, v144
	v_max_f32_e32 v145, v145, v145
	v_max_f32_e32 v146, v146, v146
	v_max_f32_e32 v147, v147, v147
	v_max_f32_e32 v6, v6, v144
	v_max_f32_e32 v7, v7, v145
	v_max_f32_e32 v6, v6, v146
	v_max_f32_e32 v7, v7, v147
	global_load_dwordx4 v[144:147], v21, s[38:39] offset:640
	s_waitcnt vmcnt(15)
	v_max_f32_e32 v148, v148, v148
	v_max_f32_e32 v149, v149, v149
	v_max_f32_e32 v150, v150, v150
	v_max_f32_e32 v151, v151, v151
	v_max_f32_e32 v6, v6, v148
	v_max_f32_e32 v7, v7, v149
	v_max_f32_e32 v6, v6, v150
	v_max_f32_e32 v7, v7, v151
	global_load_dwordx4 v[148:151], v21, s[38:39] offset:656
	s_waitcnt vmcnt(15)
	v_max_f32_e32 v152, v152, v152
	v_max_f32_e32 v153, v153, v153
	v_max_f32_e32 v154, v154, v154
	v_max_f32_e32 v155, v155, v155
	v_max_f32_e32 v6, v6, v152
	v_max_f32_e32 v7, v7, v153
	v_max_f32_e32 v6, v6, v154
	v_max_f32_e32 v7, v7, v155
	global_load_dwordx4 v[152:155], v21, s[38:39] offset:672
	s_waitcnt vmcnt(15)
	v_max_f32_e32 v156, v156, v156
	v_max_f32_e32 v157, v157, v157
	v_max_f32_e32 v158, v158, v158
	v_max_f32_e32 v159, v159, v159
	v_max_f32_e32 v6, v6, v156
	v_max_f32_e32 v7, v7, v157
	v_max_f32_e32 v6, v6, v158
	v_max_f32_e32 v7, v7, v159
	global_load_dwordx4 v[156:159], v21, s[38:39] offset:688
	s_waitcnt vmcnt(15)
	v_max_f32_e32 v160, v160, v160
	v_max_f32_e32 v161, v161, v161
	v_max_f32_e32 v162, v162, v162
	v_max_f32_e32 v163, v163, v163
	v_max_f32_e32 v6, v6, v160
	v_max_f32_e32 v7, v7, v161
	v_max_f32_e32 v6, v6, v162
	v_max_f32_e32 v7, v7, v163
	global_load_dwordx4 v[160:163], v21, s[38:39] offset:704
	s_waitcnt vmcnt(15)
	v_max_f32_e32 v164, v164, v164
	v_max_f32_e32 v165, v165, v165
	v_max_f32_e32 v166, v166, v166
	v_max_f32_e32 v167, v167, v167
	v_max_f32_e32 v6, v6, v164
	v_max_f32_e32 v7, v7, v165
	v_max_f32_e32 v6, v6, v166
	v_max_f32_e32 v7, v7, v167
	global_load_dwordx4 v[164:167], v21, s[38:39] offset:720
	s_waitcnt vmcnt(15)
	v_max_f32_e32 v168, v168, v168
	v_max_f32_e32 v169, v169, v169
	v_max_f32_e32 v170, v170, v170
	v_max_f32_e32 v171, v171, v171
	v_max_f32_e32 v6, v6, v168
	v_max_f32_e32 v7, v7, v169
	v_max_f32_e32 v6, v6, v170
	v_max_f32_e32 v7, v7, v171
	global_load_dwordx4 v[168:171], v21, s[38:39] offset:736
	s_waitcnt vmcnt(15)
	v_max_f32_e32 v172, v172, v172
	v_max_f32_e32 v173, v173, v173
	v_max_f32_e32 v174, v174, v174
	v_max_f32_e32 v175, v175, v175
	v_max_f32_e32 v6, v6, v172
	v_max_f32_e32 v7, v7, v173
	v_max_f32_e32 v6, v6, v174
	v_max_f32_e32 v7, v7, v175
	global_load_dwordx4 v[172:175], v21, s[38:39] offset:752
	s_waitcnt vmcnt(15)
	v_max_f32_e32 v112, v112, v112
	v_max_f32_e32 v113, v113, v113
	v_max_f32_e32 v114, v114, v114
	v_max_f32_e32 v115, v115, v115
	v_max_f32_e32 v6, v6, v112
	v_max_f32_e32 v7, v7, v113
	v_max_f32_e32 v6, v6, v114
	v_max_f32_e32 v7, v7, v115
	global_load_dwordx4 v[112:115], v21, s[38:39] offset:768
	s_waitcnt vmcnt(15)
; __device__ void phase0(const Params& p, unsigned char* smem) {
;     ...
;             if (tid < 2) {
;                 const int l = tid; float mqa = 0.f, mka = 0.f, mqb = 0.f, mkb = 0.f, mb = 0.f;
;                 for (int i = 0; i < 64; ++i) { mqa = fmaxf(mqa, fabsf(p.q_norm_a[l * 64 + i])); mka = fmaxf(mka, fabsf(p.k_norm_a[l * 64 + i]));
;                     mqb = fmaxf(mqb, fabsf(p.q_norm_b[l * 64 + i])); mkb = fmaxf(mkb, fabsf(p.k_norm_b[l * 64 + i])); }
;                 for (int i = 0; i < 32 * 12; ++i) mb = fmaxf(mb, p.rel_bias[i]);
;                 float* bd = (float*)(p.ws + WS_BND);
;                 bd[l] = 8.f * mqa * mka * LOG2E; bd[2 + l] = (8.f * mqb * mkb + mb) * LOG2E;
;             }
	v_max_f32_e32 v116, v116, v116
	v_max_f32_e32 v117, v117, v117
	v_max_f32_e32 v118, v118, v118
	v_max_f32_e32 v119, v119, v119
	v_max_f32_e32 v6, v6, v116
	v_max_f32_e32 v7, v7, v117
	v_max_f32_e32 v6, v6, v118
	v_max_f32_e32 v7, v7, v119
	global_load_dwordx4 v[116:119], v21, s[38:39] offset:784
	s_waitcnt vmcnt(15)
	v_max_f32_e32 v120, v120, v120
	v_max_f32_e32 v121, v121, v121
	v_max_f32_e32 v122, v122, v122
	v_max_f32_e32 v123, v123, v123
	v_max_f32_e32 v6, v6, v120
	v_max_f32_e32 v7, v7, v121
	v_max_f32_e32 v6, v6, v122
	v_max_f32_e32 v7, v7, v123
	global_load_dwordx4 v[120:123], v21, s[38:39] offset:800
	s_waitcnt vmcnt(15)
	v_max_f32_e32 v124, v124, v124
	v_max_f32_e32 v125, v125, v125
	v_max_f32_e32 v126, v126, v126
	v_max_f32_e32 v127, v127, v127
	v_max_f32_e32 v6, v6, v124
	v_max_f32_e32 v7, v7, v125
	v_max_f32_e32 v6, v6, v126
	v_max_f32_e32 v7, v7, v127
	global_load_dwordx4 v[124:127], v21, s[38:39] offset:816
	s_waitcnt vmcnt(15)
	v_max_f32_e32 v128, v128, v128
	v_max_f32_e32 v129, v129, v129
	v_max_f32_e32 v130, v130, v130
	v_max_f32_e32 v131, v131, v131
	v_max_f32_e32 v6, v6, v128
	v_max_f32_e32 v7, v7, v129
	v_max_f32_e32 v6, v6, v130
	v_max_f32_e32 v7, v7, v131
	global_load_dwordx4 v[128:131], v21, s[38:39] offset:832
	s_waitcnt vmcnt(15)
	v_max_f32_e32 v132, v132, v132
	v_max_f32_e32 v133, v133, v133
	v_max_f32_e32 v134, v134, v134
	v_max_f32_e32 v135, v135, v135
	v_max_f32_e32 v6, v6, v132
	v_max_f32_e32 v7, v7, v133
	v_max_f32_e32 v6, v6, v134
	v_max_f32_e32 v7, v7, v135
	global_load_dwordx4 v[132:135], v21, s[38:39] offset:848
	s_waitcnt vmcnt(15)
	v_max_f32_e32 v136, v136, v136
	v_max_f32_e32 v137, v137, v137
	v_max_f32_e32 v138, v138, v138
	v_max_f32_e32 v139, v139, v139
	v_max_f32_e32 v6, v6, v136
	v_max_f32_e32 v7, v7, v137
	v_max_f32_e32 v6, v6, v138
	v_max_f32_e32 v7, v7, v139
	global_load_dwordx4 v[136:139], v21, s[38:39] offset:864
	s_waitcnt vmcnt(15)
	v_max_f32_e32 v140, v140, v140
	v_max_f32_e32 v141, v141, v141
	v_max_f32_e32 v142, v142, v142
	v_max_f32_e32 v143, v143, v143
	v_max_f32_e32 v6, v6, v140
	v_max_f32_e32 v7, v7, v141
	v_max_f32_e32 v6, v6, v142
	v_max_f32_e32 v7, v7, v143
	global_load_dwordx4 v[140:143], v21, s[38:39] offset:880
	s_waitcnt vmcnt(15)
	v_max_f32_e32 v144, v144, v144
	v_max_f32_e32 v145, v145, v145
	v_max_f32_e32 v146, v146, v146
	v_max_f32_e32 v147, v147, v147
	v_max_f32_e32 v6, v6, v144
	v_max_f32_e32 v7, v7, v145
	v_max_f32_e32 v6, v6, v146
	v_max_f32_e32 v7, v7, v147
	global_load_dwordx4 v[144:147], v21, s[38:39] offset:896
	s_waitcnt vmcnt(15)
	v_max_f32_e32 v148, v148, v148
	v_max_f32_e32 v149, v149, v149
	v_max_f32_e32 v150, v150, v150
	v_max_f32_e32 v151, v151, v151
	v_max_f32_e32 v6, v6, v148
	v_max_f32_e32 v7, v7, v149
	v_max_f32_e32 v6, v6, v150
	v_max_f32_e32 v7, v7, v151
	global_load_dwordx4 v[148:151], v21, s[38:39] offset:912
	s_waitcnt vmcnt(15)
	v_max_f32_e32 v152, v152, v152
	v_max_f32_e32 v153, v153, v153
	v_max_f32_e32 v154, v154, v154
	v_max_f32_e32 v155, v155, v155
	v_max_f32_e32 v6, v6, v152
	v_max_f32_e32 v7, v7, v153
	v_max_f32_e32 v6, v6, v154
	v_max_f32_e32 v7, v7, v155
	global_load_dwordx4 v[152:155], v21, s[38:39] offset:928
	s_waitcnt vmcnt(15)
	v_max_f32_e32 v156, v156, v156
	v_max_f32_e32 v157, v157, v157
	v_max_f32_e32 v158, v158, v158
	v_max_f32_e32 v159, v159, v159
	v_max_f32_e32 v6, v6, v156
	v_max_f32_e32 v7, v7, v157
	v_max_f32_e32 v6, v6, v158
	v_max_f32_e32 v7, v7, v159
	global_load_dwordx4 v[156:159], v21, s[38:39] offset:944
	s_waitcnt vmcnt(15)
	v_max_f32_e32 v160, v160, v160
	v_max_f32_e32 v161, v161, v161
	v_max_f32_e32 v162, v162, v162
	v_max_f32_e32 v163, v163, v163
	v_max_f32_e32 v6, v6, v160
	v_max_f32_e32 v7, v7, v161
	v_max_f32_e32 v6, v6, v162
	v_max_f32_e32 v7, v7, v163
	global_load_dwordx4 v[160:163], v21, s[38:39] offset:960
	s_waitcnt vmcnt(15)
	v_max_f32_e32 v164, v164, v164
	v_max_f32_e32 v165, v165, v165
	v_max_f32_e32 v166, v166, v166
	v_max_f32_e32 v167, v167, v167
	v_max_f32_e32 v6, v6, v164
	v_max_f32_e32 v7, v7, v165
	v_max_f32_e32 v6, v6, v166
	v_max_f32_e32 v7, v7, v167
	global_load_dwordx4 v[164:167], v21, s[38:39] offset:976
	s_waitcnt vmcnt(15)
	v_max_f32_e32 v168, v168, v168
	v_max_f32_e32 v169, v169, v169
	v_max_f32_e32 v170, v170, v170
	v_max_f32_e32 v171, v171, v171
	v_max_f32_e32 v6, v6, v168
	v_max_f32_e32 v7, v7, v169
	v_max_f32_e32 v6, v6, v170
	v_max_f32_e32 v7, v7, v171
	global_load_dwordx4 v[168:171], v21, s[38:39] offset:992
	s_waitcnt vmcnt(15)
	v_max_f32_e32 v172, v172, v172
	v_max_f32_e32 v173, v173, v173
	v_max_f32_e32 v174, v174, v174
	v_max_f32_e32 v175, v175, v175
	v_max_f32_e32 v6, v6, v172
	v_max_f32_e32 v7, v7, v173
	v_max_f32_e32 v6, v6, v174
	v_max_f32_e32 v7, v7, v175
	global_load_dwordx4 v[172:175], v21, s[38:39] offset:1008
	s_waitcnt vmcnt(15)
	v_max_f32_e32 v112, v112, v112
	v_max_f32_e32 v113, v113, v113
	v_max_f32_e32 v114, v114, v114
	v_max_f32_e32 v115, v115, v115
	v_max_f32_e32 v6, v6, v112
	v_max_f32_e32 v7, v7, v113
	v_max_f32_e32 v6, v6, v114
	v_max_f32_e32 v7, v7, v115
	global_load_dwordx4 v[112:115], v21, s[38:39] offset:1024
	s_waitcnt vmcnt(15)
	v_max_f32_e32 v116, v116, v116
	v_max_f32_e32 v117, v117, v117
	v_max_f32_e32 v118, v118, v118
	v_max_f32_e32 v119, v119, v119
	v_max_f32_e32 v6, v6, v116
	v_max_f32_e32 v7, v7, v117
	v_max_f32_e32 v6, v6, v118
	v_max_f32_e32 v7, v7, v119
	global_load_dwordx4 v[116:119], v21, s[38:39] offset:1040
	s_waitcnt vmcnt(15)
	v_max_f32_e32 v120, v120, v120
	v_max_f32_e32 v121, v121, v121
	v_max_f32_e32 v122, v122, v122
	v_max_f32_e32 v123, v123, v123
	v_max_f32_e32 v6, v6, v120
	v_max_f32_e32 v7, v7, v121
	v_max_f32_e32 v6, v6, v122
	v_max_f32_e32 v7, v7, v123
	global_load_dwordx4 v[120:123], v21, s[38:39] offset:1056
	s_waitcnt vmcnt(15)
; __device__ void phase0(const Params& p, unsigned char* smem) {
;     ...
;             if (tid < 2) {
;                 const int l = tid; float mqa = 0.f, mka = 0.f, mqb = 0.f, mkb = 0.f, mb = 0.f;
;                 for (int i = 0; i < 64; ++i) { mqa = fmaxf(mqa, fabsf(p.q_norm_a[l * 64 + i])); mka = fmaxf(mka, fabsf(p.k_norm_a[l * 64 + i]));
;                     mqb = fmaxf(mqb, fabsf(p.q_norm_b[l * 64 + i])); mkb = fmaxf(mkb, fabsf(p.k_norm_b[l * 64 + i])); }
;                 for (int i = 0; i < 32 * 12; ++i) mb = fmaxf(mb, p.rel_bias[i]);
;                 float* bd = (float*)(p.ws + WS_BND);
;                 bd[l] = 8.f * mqa * mka * LOG2E; bd[2 + l] = (8.f * mqb * mkb + mb) * LOG2E;
;             }
	v_max_f32_e32 v124, v124, v124
	v_max_f32_e32 v125, v125, v125
	v_max_f32_e32 v126, v126, v126
	v_max_f32_e32 v127, v127, v127
	v_max_f32_e32 v6, v6, v124
	v_max_f32_e32 v7, v7, v125
	v_max_f32_e32 v6, v6, v126
	v_max_f32_e32 v7, v7, v127
	global_load_dwordx4 v[124:127], v21, s[38:39] offset:1072
	s_waitcnt vmcnt(15)
	v_max_f32_e32 v128, v128, v128
	v_max_f32_e32 v129, v129, v129
	v_max_f32_e32 v130, v130, v130
	v_max_f32_e32 v131, v131, v131
	v_max_f32_e32 v6, v6, v128
	v_max_f32_e32 v7, v7, v129
	v_max_f32_e32 v6, v6, v130
	v_max_f32_e32 v7, v7, v131
	global_load_dwordx4 v[128:131], v21, s[38:39] offset:1088
	s_waitcnt vmcnt(15)
	v_max_f32_e32 v132, v132, v132
	v_max_f32_e32 v133, v133, v133
	v_max_f32_e32 v134, v134, v134
	v_max_f32_e32 v135, v135, v135
	v_max_f32_e32 v6, v6, v132
	v_max_f32_e32 v7, v7, v133
	v_max_f32_e32 v6, v6, v134
	v_max_f32_e32 v7, v7, v135
	global_load_dwordx4 v[132:135], v21, s[38:39] offset:1104
	s_waitcnt vmcnt(15)
	v_max_f32_e32 v136, v136, v136
	v_max_f32_e32 v137, v137, v137
	v_max_f32_e32 v138, v138, v138
	v_max_f32_e32 v139, v139, v139
	v_max_f32_e32 v6, v6, v136
	v_max_f32_e32 v7, v7, v137
	v_max_f32_e32 v6, v6, v138
	v_max_f32_e32 v7, v7, v139
	global_load_dwordx4 v[136:139], v21, s[38:39] offset:1120
	s_waitcnt vmcnt(15)
	v_max_f32_e32 v140, v140, v140
	v_max_f32_e32 v141, v141, v141
	v_max_f32_e32 v142, v142, v142
	v_max_f32_e32 v143, v143, v143
	v_max_f32_e32 v6, v6, v140
	v_max_f32_e32 v7, v7, v141
	v_max_f32_e32 v6, v6, v142
	v_max_f32_e32 v7, v7, v143
	global_load_dwordx4 v[140:143], v21, s[38:39] offset:1136
	s_waitcnt vmcnt(15)
	v_max_f32_e32 v144, v144, v144
	v_max_f32_e32 v145, v145, v145
	v_max_f32_e32 v146, v146, v146
	v_max_f32_e32 v147, v147, v147
	v_max_f32_e32 v6, v6, v144
	v_max_f32_e32 v7, v7, v145
	v_max_f32_e32 v6, v6, v146
	v_max_f32_e32 v7, v7, v147
	global_load_dwordx4 v[144:147], v21, s[38:39] offset:1152
	s_waitcnt vmcnt(15)
	v_max_f32_e32 v148, v148, v148
	v_max_f32_e32 v149, v149, v149
	v_max_f32_e32 v150, v150, v150
	v_max_f32_e32 v151, v151, v151
	v_max_f32_e32 v6, v6, v148
	v_max_f32_e32 v7, v7, v149
	v_max_f32_e32 v6, v6, v150
	v_max_f32_e32 v7, v7, v151
	global_load_dwordx4 v[148:151], v21, s[38:39] offset:1168
	s_waitcnt vmcnt(15)
	v_max_f32_e32 v152, v152, v152
	v_max_f32_e32 v153, v153, v153
	v_max_f32_e32 v154, v154, v154
	v_max_f32_e32 v155, v155, v155
	v_max_f32_e32 v6, v6, v152
	v_max_f32_e32 v7, v7, v153
	v_max_f32_e32 v6, v6, v154
	v_max_f32_e32 v7, v7, v155
	global_load_dwordx4 v[152:155], v21, s[38:39] offset:1184
	s_waitcnt vmcnt(15)
	v_max_f32_e32 v156, v156, v156
	v_max_f32_e32 v157, v157, v157
	v_max_f32_e32 v158, v158, v158
	v_max_f32_e32 v159, v159, v159
	v_max_f32_e32 v6, v6, v156
	v_max_f32_e32 v7, v7, v157
	v_max_f32_e32 v6, v6, v158
	v_max_f32_e32 v7, v7, v159
	global_load_dwordx4 v[156:159], v21, s[38:39] offset:1200
	s_waitcnt vmcnt(15)
	v_max_f32_e32 v160, v160, v160
	v_max_f32_e32 v161, v161, v161
	v_max_f32_e32 v162, v162, v162
	v_max_f32_e32 v163, v163, v163
	v_max_f32_e32 v6, v6, v160
	v_max_f32_e32 v7, v7, v161
	v_max_f32_e32 v6, v6, v162
	v_max_f32_e32 v7, v7, v163
	global_load_dwordx4 v[160:163], v21, s[38:39] offset:1216
	s_waitcnt vmcnt(15)
	v_max_f32_e32 v164, v164, v164
	v_max_f32_e32 v165, v165, v165
	v_max_f32_e32 v166, v166, v166
	v_max_f32_e32 v167, v167, v167
	v_max_f32_e32 v6, v6, v164
	v_max_f32_e32 v7, v7, v165
	v_max_f32_e32 v6, v6, v166
	v_max_f32_e32 v7, v7, v167
	global_load_dwordx4 v[164:167], v21, s[38:39] offset:1232
	s_waitcnt vmcnt(15)
	v_max_f32_e32 v168, v168, v168
	v_max_f32_e32 v169, v169, v169
	v_max_f32_e32 v170, v170, v170
	v_max_f32_e32 v171, v171, v171
	v_max_f32_e32 v6, v6, v168
	v_max_f32_e32 v7, v7, v169
	v_max_f32_e32 v6, v6, v170
	v_max_f32_e32 v7, v7, v171
	global_load_dwordx4 v[168:171], v21, s[38:39] offset:1248
	s_waitcnt vmcnt(15)
	v_max_f32_e32 v172, v172, v172
	v_max_f32_e32 v173, v173, v173
	v_max_f32_e32 v174, v174, v174
	v_max_f32_e32 v175, v175, v175
	v_max_f32_e32 v6, v6, v172
	v_max_f32_e32 v7, v7, v173
	v_max_f32_e32 v6, v6, v174
	v_max_f32_e32 v7, v7, v175
	global_load_dwordx4 v[172:175], v21, s[38:39] offset:1264
	s_waitcnt vmcnt(15)
	v_max_f32_e32 v112, v112, v112
	v_max_f32_e32 v113, v113, v113
	v_max_f32_e32 v114, v114, v114
	v_max_f32_e32 v115, v115, v115
	v_max_f32_e32 v6, v6, v112
	v_max_f32_e32 v7, v7, v113
	v_max_f32_e32 v6, v6, v114
	v_max_f32_e32 v7, v7, v115
	global_load_dwordx4 v[112:115], v21, s[38:39] offset:1280
	s_waitcnt vmcnt(15)
	v_max_f32_e32 v116, v116, v116
	v_max_f32_e32 v117, v117, v117
	v_max_f32_e32 v118, v118, v118
	v_max_f32_e32 v119, v119, v119
	v_max_f32_e32 v6, v6, v116
	v_max_f32_e32 v7, v7, v117
	v_max_f32_e32 v6, v6, v118
	v_max_f32_e32 v7, v7, v119
	global_load_dwordx4 v[116:119], v21, s[38:39] offset:1296
	s_waitcnt vmcnt(15)
	v_max_f32_e32 v120, v120, v120
	v_max_f32_e32 v121, v121, v121
	v_max_f32_e32 v122, v122, v122
	v_max_f32_e32 v123, v123, v123
	v_max_f32_e32 v6, v6, v120
	v_max_f32_e32 v7, v7, v121
	v_max_f32_e32 v6, v6, v122
	v_max_f32_e32 v7, v7, v123
	global_load_dwordx4 v[120:123], v21, s[38:39] offset:1312
	s_waitcnt vmcnt(15)
	v_max_f32_e32 v124, v124, v124
	v_max_f32_e32 v125, v125, v125
	v_max_f32_e32 v126, v126, v126
	v_max_f32_e32 v127, v127, v127
	v_max_f32_e32 v6, v6, v124
	v_max_f32_e32 v7, v7, v125
	v_max_f32_e32 v6, v6, v126
	v_max_f32_e32 v7, v7, v127
	global_load_dwordx4 v[124:127], v21, s[38:39] offset:1328
	s_waitcnt vmcnt(15)
	v_max_f32_e32 v128, v128, v128
	v_max_f32_e32 v129, v129, v129
	v_max_f32_e32 v130, v130, v130
	v_max_f32_e32 v131, v131, v131
	v_max_f32_e32 v6, v6, v128
	v_max_f32_e32 v7, v7, v129
	v_max_f32_e32 v6, v6, v130
	v_max_f32_e32 v7, v7, v131
	global_load_dwordx4 v[128:131], v21, s[38:39] offset:1344
	s_waitcnt vmcnt(15)
; __device__ void phase0(const Params& p, unsigned char* smem) {
;     ...
;             if (tid < 2) {
;                 const int l = tid; float mqa = 0.f, mka = 0.f, mqb = 0.f, mkb = 0.f, mb = 0.f;
;                 for (int i = 0; i < 64; ++i) { mqa = fmaxf(mqa, fabsf(p.q_norm_a[l * 64 + i])); mka = fmaxf(mka, fabsf(p.k_norm_a[l * 64 + i]));
;                     mqb = fmaxf(mqb, fabsf(p.q_norm_b[l * 64 + i])); mkb = fmaxf(mkb, fabsf(p.k_norm_b[l * 64 + i])); }
;                 for (int i = 0; i < 32 * 12; ++i) mb = fmaxf(mb, p.rel_bias[i]);
;                 float* bd = (float*)(p.ws + WS_BND);
;                 bd[l] = 8.f * mqa * mka * LOG2E; bd[2 + l] = (8.f * mqb * mkb + mb) * LOG2E;
;             }
	v_max_f32_e32 v132, v132, v132
	v_max_f32_e32 v133, v133, v133
	v_max_f32_e32 v134, v134, v134
	v_max_f32_e32 v135, v135, v135
	v_max_f32_e32 v6, v6, v132
	v_max_f32_e32 v7, v7, v133
	v_max_f32_e32 v6, v6, v134
	v_max_f32_e32 v7, v7, v135
	global_load_dwordx4 v[132:135], v21, s[38:39] offset:1360
	s_waitcnt vmcnt(15)
	v_max_f32_e32 v136, v136, v136
	v_max_f32_e32 v137, v137, v137
	v_max_f32_e32 v138, v138, v138
	v_max_f32_e32 v139, v139, v139
	v_max_f32_e32 v6, v6, v136
	v_max_f32_e32 v7, v7, v137
	v_max_f32_e32 v6, v6, v138
	v_max_f32_e32 v7, v7, v139
	global_load_dwordx4 v[136:139], v21, s[38:39] offset:1376
	s_waitcnt vmcnt(15)
	v_max_f32_e32 v140, v140, v140
	v_max_f32_e32 v141, v141, v141
	v_max_f32_e32 v142, v142, v142
	v_max_f32_e32 v143, v143, v143
	v_max_f32_e32 v6, v6, v140
	v_max_f32_e32 v7, v7, v141
	v_max_f32_e32 v6, v6, v142
	v_max_f32_e32 v7, v7, v143
	global_load_dwordx4 v[140:143], v21, s[38:39] offset:1392
	s_waitcnt vmcnt(15)
	v_max_f32_e32 v144, v144, v144
	v_max_f32_e32 v145, v145, v145
	v_max_f32_e32 v146, v146, v146
	v_max_f32_e32 v147, v147, v147
	v_max_f32_e32 v6, v6, v144
	v_max_f32_e32 v7, v7, v145
	v_max_f32_e32 v6, v6, v146
	v_max_f32_e32 v7, v7, v147
	global_load_dwordx4 v[144:147], v21, s[38:39] offset:1408
	s_waitcnt vmcnt(15)
	v_max_f32_e32 v148, v148, v148
	v_max_f32_e32 v149, v149, v149
	v_max_f32_e32 v150, v150, v150
	v_max_f32_e32 v151, v151, v151
	v_max_f32_e32 v6, v6, v148
	v_max_f32_e32 v7, v7, v149
	v_max_f32_e32 v6, v6, v150
	v_max_f32_e32 v7, v7, v151
	global_load_dwordx4 v[148:151], v21, s[38:39] offset:1424
	s_waitcnt vmcnt(15)
	v_max_f32_e32 v152, v152, v152
	v_max_f32_e32 v153, v153, v153
	v_max_f32_e32 v154, v154, v154
	v_max_f32_e32 v155, v155, v155
	v_max_f32_e32 v6, v6, v152
	v_max_f32_e32 v7, v7, v153
	v_max_f32_e32 v6, v6, v154
	v_max_f32_e32 v7, v7, v155
	global_load_dwordx4 v[152:155], v21, s[38:39] offset:1440
	s_waitcnt vmcnt(15)
	v_max_f32_e32 v156, v156, v156
	v_max_f32_e32 v157, v157, v157
	v_max_f32_e32 v158, v158, v158
	v_max_f32_e32 v159, v159, v159
	v_max_f32_e32 v6, v6, v156
	v_max_f32_e32 v7, v7, v157
	v_max_f32_e32 v6, v6, v158
	v_max_f32_e32 v7, v7, v159
	global_load_dwordx4 v[156:159], v21, s[38:39] offset:1456
	s_waitcnt vmcnt(15)
	v_max_f32_e32 v160, v160, v160
	v_max_f32_e32 v161, v161, v161
	v_max_f32_e32 v162, v162, v162
	v_max_f32_e32 v163, v163, v163
	v_max_f32_e32 v6, v6, v160
	v_max_f32_e32 v7, v7, v161
	v_max_f32_e32 v6, v6, v162
	v_max_f32_e32 v7, v7, v163
	global_load_dwordx4 v[160:163], v21, s[38:39] offset:1472
	s_waitcnt vmcnt(15)
	v_max_f32_e32 v164, v164, v164
	v_max_f32_e32 v165, v165, v165
	v_max_f32_e32 v166, v166, v166
	v_max_f32_e32 v167, v167, v167
	v_max_f32_e32 v6, v6, v164
	v_max_f32_e32 v7, v7, v165
	v_max_f32_e32 v6, v6, v166
	v_max_f32_e32 v7, v7, v167
	global_load_dwordx4 v[164:167], v21, s[38:39] offset:1488
	s_waitcnt vmcnt(15)
	v_max_f32_e32 v168, v168, v168
	v_max_f32_e32 v169, v169, v169
	v_max_f32_e32 v170, v170, v170
	v_max_f32_e32 v171, v171, v171
	v_max_f32_e32 v6, v6, v168
	v_max_f32_e32 v7, v7, v169
	v_max_f32_e32 v6, v6, v170
	v_max_f32_e32 v7, v7, v171
	global_load_dwordx4 v[168:171], v21, s[38:39] offset:1504
	s_waitcnt vmcnt(15)
	v_max_f32_e32 v172, v172, v172
	v_max_f32_e32 v173, v173, v173
	v_max_f32_e32 v174, v174, v174
	v_max_f32_e32 v175, v175, v175
	v_max_f32_e32 v6, v6, v172
	v_max_f32_e32 v7, v7, v173
	v_max_f32_e32 v6, v6, v174
	v_max_f32_e32 v7, v7, v175
	global_load_dwordx4 v[172:175], v21, s[38:39] offset:1520
	s_waitcnt vmcnt(15)
	v_max_f32_e32 v112, v112, v112
	v_max_f32_e32 v113, v113, v113
	v_max_f32_e32 v114, v114, v114
	v_max_f32_e32 v115, v115, v115
	v_max_f32_e32 v6, v6, v112
	v_max_f32_e32 v7, v7, v113
	v_max_f32_e32 v6, v6, v114
	v_max_f32_e32 v7, v7, v115
	s_waitcnt vmcnt(14)
; __device__ void phase0(const Params& p, unsigned char* smem) {
;     ...
;             if (tid < 2) {
;                 const int l = tid; float mqa = 0.f, mka = 0.f, mqb = 0.f, mkb = 0.f, mb = 0.f;
;                 for (int i = 0; i < 64; ++i) { mqa = fmaxf(mqa, fabsf(p.q_norm_a[l * 64 + i])); mka = fmaxf(mka, fabsf(p.k_norm_a[l * 64 + i]));
;                     mqb = fmaxf(mqb, fabsf(p.q_norm_b[l * 64 + i])); mkb = fmaxf(mkb, fabsf(p.k_norm_b[l * 64 + i])); }
;                 for (int i = 0; i < 32 * 12; ++i) mb = fmaxf(mb, p.rel_bias[i]);
;                 float* bd = (float*)(p.ws + WS_BND);
;                 bd[l] = 8.f * mqa * mka * LOG2E; bd[2 + l] = (8.f * mqb * mkb + mb) * LOG2E;
;             }
	v_max_f32_e32 v116, v116, v116
	v_max_f32_e32 v117, v117, v117
	v_max_f32_e32 v118, v118, v118
	v_max_f32_e32 v119, v119, v119
	v_max_f32_e32 v6, v6, v116
	v_max_f32_e32 v7, v7, v117
	v_max_f32_e32 v6, v6, v118
	v_max_f32_e32 v7, v7, v119
	s_waitcnt vmcnt(13)
	v_max_f32_e32 v120, v120, v120
	v_max_f32_e32 v121, v121, v121
	v_max_f32_e32 v122, v122, v122
	v_max_f32_e32 v123, v123, v123
	v_max_f32_e32 v6, v6, v120
	v_max_f32_e32 v7, v7, v121
	v_max_f32_e32 v6, v6, v122
	v_max_f32_e32 v7, v7, v123
	s_waitcnt vmcnt(12)
	v_max_f32_e32 v124, v124, v124
	v_max_f32_e32 v125, v125, v125
	v_max_f32_e32 v126, v126, v126
	v_max_f32_e32 v127, v127, v127
	v_max_f32_e32 v6, v6, v124
	v_max_f32_e32 v7, v7, v125
	v_max_f32_e32 v6, v6, v126
	v_max_f32_e32 v7, v7, v127
	s_waitcnt vmcnt(11)
	v_max_f32_e32 v128, v128, v128
	v_max_f32_e32 v129, v129, v129
	v_max_f32_e32 v130, v130, v130
	v_max_f32_e32 v131, v131, v131
	v_max_f32_e32 v6, v6, v128
	v_max_f32_e32 v7, v7, v129
	v_max_f32_e32 v6, v6, v130
	v_max_f32_e32 v7, v7, v131
	s_waitcnt vmcnt(10)
	v_max_f32_e32 v132, v132, v132
	v_max_f32_e32 v133, v133, v133
	v_max_f32_e32 v134, v134, v134
	v_max_f32_e32 v135, v135, v135
	v_max_f32_e32 v6, v6, v132
	v_max_f32_e32 v7, v7, v133
	v_max_f32_e32 v6, v6, v134
	v_max_f32_e32 v7, v7, v135
	s_waitcnt vmcnt(9)
	v_max_f32_e32 v136, v136, v136
	v_max_f32_e32 v137, v137, v137
	v_max_f32_e32 v138, v138, v138
	v_max_f32_e32 v139, v139, v139
	v_max_f32_e32 v6, v6, v136
	v_max_f32_e32 v7, v7, v137
	v_max_f32_e32 v6, v6, v138
	v_max_f32_e32 v7, v7, v139
	s_waitcnt vmcnt(8)
	v_max_f32_e32 v140, v140, v140
	v_max_f32_e32 v141, v141, v141
	v_max_f32_e32 v142, v142, v142
	v_max_f32_e32 v143, v143, v143
	v_max_f32_e32 v6, v6, v140
	v_max_f32_e32 v7, v7, v141
	v_max_f32_e32 v6, v6, v142
	v_max_f32_e32 v7, v7, v143
	s_waitcnt vmcnt(7)
	v_max_f32_e32 v144, v144, v144
	v_max_f32_e32 v145, v145, v145
	v_max_f32_e32 v146, v146, v146
	v_max_f32_e32 v147, v147, v147
	v_max_f32_e32 v6, v6, v144
	v_max_f32_e32 v7, v7, v145
	v_max_f32_e32 v6, v6, v146
	v_max_f32_e32 v7, v7, v147
	s_waitcnt vmcnt(6)
	v_max_f32_e32 v148, v148, v148
	v_max_f32_e32 v149, v149, v149
	v_max_f32_e32 v150, v150, v150
	v_max_f32_e32 v151, v151, v151
	v_max_f32_e32 v6, v6, v148
	v_max_f32_e32 v7, v7, v149
	v_max_f32_e32 v6, v6, v150
	v_max_f32_e32 v7, v7, v151
	s_waitcnt vmcnt(5)
	v_max_f32_e32 v152, v152, v152
	v_max_f32_e32 v153, v153, v153
	v_max_f32_e32 v154, v154, v154
	v_max_f32_e32 v155, v155, v155
	v_max_f32_e32 v6, v6, v152
	v_max_f32_e32 v7, v7, v153
	v_max_f32_e32 v6, v6, v154
	v_max_f32_e32 v7, v7, v155
	s_waitcnt vmcnt(4)
	v_max_f32_e32 v156, v156, v156
	v_max_f32_e32 v157, v157, v157
	v_max_f32_e32 v158, v158, v158
	v_max_f32_e32 v159, v159, v159
	v_max_f32_e32 v6, v6, v156
	v_max_f32_e32 v7, v7, v157
	v_max_f32_e32 v6, v6, v158
	v_max_f32_e32 v7, v7, v159
	s_waitcnt vmcnt(3)
	v_max_f32_e32 v160, v160, v160
	v_max_f32_e32 v161, v161, v161
	v_max_f32_e32 v162, v162, v162
	v_max_f32_e32 v163, v163, v163
	v_max_f32_e32 v6, v6, v160
	v_max_f32_e32 v7, v7, v161
	v_max_f32_e32 v6, v6, v162
	v_max_f32_e32 v7, v7, v163
	s_waitcnt vmcnt(2)
	v_max_f32_e32 v164, v164, v164
	v_max_f32_e32 v165, v165, v165
	v_max_f32_e32 v166, v166, v166
	v_max_f32_e32 v167, v167, v167
	v_max_f32_e32 v6, v6, v164
	v_max_f32_e32 v7, v7, v165
	v_max_f32_e32 v6, v6, v166
	v_max_f32_e32 v7, v7, v167
	s_waitcnt vmcnt(1)
	v_max_f32_e32 v168, v168, v168
	v_max_f32_e32 v169, v169, v169
	v_max_f32_e32 v170, v170, v170
	v_max_f32_e32 v171, v171, v171
	v_max_f32_e32 v6, v6, v168
	v_max_f32_e32 v7, v7, v169
	v_max_f32_e32 v6, v6, v170
	v_max_f32_e32 v7, v7, v171
	s_waitcnt vmcnt(0)
	v_max_f32_e32 v172, v172, v172
	v_max_f32_e32 v173, v173, v173
	v_max_f32_e32 v174, v174, v174
	v_max_f32_e32 v175, v175, v175
	v_max_f32_e32 v6, v6, v172
	v_max_f32_e32 v7, v7, v173
	v_max_f32_e32 v6, v6, v174
	v_max_f32_e32 v7, v7, v175
	v_max_f32_e32 v6, v6, v7
	s_branch .LBB0_141
